# v5 + canonicalize-max peephole (fmaxf sNaN-quieting v_max removed before max(0,x)), hazard nops re-derived
# speedup vs baseline: 1.0227x; 1.0182x over previous
; DI unsigned pk_bf16(float a, float b) { f32x2 v = {a, b}; bf2_t r = __builtin_convertvector(v, bf2_t); return __builtin_bit_cast(unsigned, r); }
;     DI void operator()(const pg8::f32x4 (&acc)[2][2][4][2], const pg8::Unit& u, int wr, int wc, int fr, int fq) const {
;         const int row0 = u.pm * 256 + wr * 64 + fr, col0 = u.pn * 256 + wc * 32 + 8 * fq;
; #pragma unroll
;         for (int ai = 0; ai < 2; ++ai)
; #pragma unroll
;             for (int m = 0; m < 4; ++m) {
;                 const int row = row0 + ai * 128 + m * 16;
;                 bf16_t* rp = U + (size_t)row * 4096 + col0;
; #pragma unroll
;                 for (int bj = 0; bj < 2; ++bj) {
;                     float v[8];
; #pragma unroll
;                     for (int n = 0; n < 2; ++n)
; #pragma unroll
;                         for (int e = 0; e < 4; ++e) { const float t = fmaxf(acc[ai][bj][m][n][e], 0.f); v[4 * n + e] = t * t; }
;                     u32x4 w; w.x = pk_bf16(v[0], v[1]); w.y = pk_bf16(v[2], v[3]); w.z = pk_bf16(v[4], v[5]); w.w = pk_bf16(v[6], v[7]);
;                     *(u32x4*)(rp + bj * 128) = w;
;                 }
;             }
.LBB0_1475:
	v_lshl_add_u32 v154, s28, 8, v1
	v_lshl_or_b32 v146, s57, 8, v149
	v_ashrrev_i32_e32 v155, 31, v154
	v_ashrrev_i32_e32 v147, 31, v146
	v_lshlrev_b64 v[156:157], 13, v[154:155]
	v_lshl_add_u64 v[156:157], s[66:67], 0, v[156:157]
	v_lshlrev_b64 v[158:159], 1, v[146:147]
	v_max_f32_e32 v122, 0, v122
	v_max_f32_e32 v123, 0, v123
	v_lshl_add_u64 v[146:147], v[156:157], 0, v[158:159]
	v_pk_mul_f32 v[156:157], v[122:123], v[122:123]
	v_max_f32_e32 v126, 0, v126
	v_max_f32_e32 v127, 0, v127
	v_max_f32_e32 v128, 0, v128
	v_max_f32_e32 v129, 0, v129
	v_max_f32_e32 v122, 0, v124
	v_max_f32_e32 v123, 0, v125
	v_pk_mul_f32 v[126:127], v[126:127], v[126:127]
	v_pk_mul_f32 v[128:129], v[128:129], v[128:129]
	v_pk_mul_f32 v[160:161], v[122:123], v[122:123]
	v_cvt_pk_bf16_f32 v122, v126, v127
	v_cvt_pk_bf16_f32 v123, v128, v129
	v_cvt_pk_bf16_f32 v124, v156, v157
	v_cvt_pk_bf16_f32 v125, v160, v161
	v_max_f32_e32 v114, 0, v114
	v_max_f32_e32 v115, 0, v115
	global_store_dwordx4 v[146:147], v[122:125], off
	s_nop 1
	v_pk_mul_f32 v[122:123], v[114:115], v[114:115]
	v_max_f32_e32 v118, 0, v118
	v_max_f32_e32 v119, 0, v119
	v_max_f32_e32 v120, 0, v120
	v_max_f32_e32 v121, 0, v121
	v_max_f32_e32 v114, 0, v116
	v_max_f32_e32 v115, 0, v117
	v_pk_mul_f32 v[118:119], v[118:119], v[118:119]
	v_pk_mul_f32 v[120:121], v[120:121], v[120:121]
	v_pk_mul_f32 v[124:125], v[114:115], v[114:115]
	v_cvt_pk_bf16_f32 v114, v118, v119
	v_cvt_pk_bf16_f32 v115, v120, v121
	v_cvt_pk_bf16_f32 v116, v122, v123
	v_cvt_pk_bf16_f32 v117, v124, v125
	global_store_dwordx4 v[146:147], v[114:117], off offset:256
	v_max_f32_e32 v106, 0, v106
	v_max_f32_e32 v107, 0, v107
	v_or_b32_e32 v114, 16, v154
	v_ashrrev_i32_e32 v115, 31, v114
	v_pk_mul_f32 v[116:117], v[106:107], v[106:107]
	v_lshlrev_b64 v[114:115], 13, v[114:115]
	v_max_f32_e32 v110, 0, v110
	v_max_f32_e32 v111, 0, v111
	v_max_f32_e32 v112, 0, v112
	v_max_f32_e32 v113, 0, v113
	v_max_f32_e32 v106, 0, v108
	v_max_f32_e32 v107, 0, v109
	v_lshl_add_u64 v[114:115], s[66:67], 0, v[114:115]
	v_pk_mul_f32 v[110:111], v[110:111], v[110:111]
	v_pk_mul_f32 v[112:113], v[112:113], v[112:113]
	v_pk_mul_f32 v[118:119], v[106:107], v[106:107]
	v_lshl_add_u64 v[114:115], v[114:115], 0, v[158:159]
	v_cvt_pk_bf16_f32 v106, v110, v111
	v_cvt_pk_bf16_f32 v107, v112, v113
	v_cvt_pk_bf16_f32 v108, v116, v117
	v_cvt_pk_bf16_f32 v109, v118, v119
	v_max_f32_e32 v98, 0, v98
	v_max_f32_e32 v99, 0, v99
	global_store_dwordx4 v[114:115], v[106:109], off
	s_nop 1
	v_pk_mul_f32 v[106:107], v[98:99], v[98:99]
	v_max_f32_e32 v102, 0, v102
	v_max_f32_e32 v103, 0, v103
	v_max_f32_e32 v104, 0, v104
	v_max_f32_e32 v105, 0, v105
	v_max_f32_e32 v98, 0, v100
	v_max_f32_e32 v99, 0, v101
	v_pk_mul_f32 v[102:103], v[102:103], v[102:103]
	v_pk_mul_f32 v[104:105], v[104:105], v[104:105]
	v_pk_mul_f32 v[108:109], v[98:99], v[98:99]
	v_cvt_pk_bf16_f32 v98, v102, v103
	v_cvt_pk_bf16_f32 v99, v104, v105
	v_cvt_pk_bf16_f32 v100, v106, v107
	v_cvt_pk_bf16_f32 v101, v108, v109
	global_store_dwordx4 v[114:115], v[98:101], off offset:256
	v_max_f32_e32 v90, 0, v90
	v_max_f32_e32 v91, 0, v91
	v_or_b32_e32 v98, 32, v154
	v_ashrrev_i32_e32 v99, 31, v98
	v_pk_mul_f32 v[100:101], v[90:91], v[90:91]
	v_lshlrev_b64 v[98:99], 13, v[98:99]
	v_max_f32_e32 v94, 0, v94
	v_max_f32_e32 v95, 0, v95
	v_max_f32_e32 v96, 0, v96
	v_max_f32_e32 v97, 0, v97
	v_max_f32_e32 v90, 0, v92
	v_max_f32_e32 v91, 0, v93
	v_lshl_add_u64 v[98:99], s[66:67], 0, v[98:99]
	v_pk_mul_f32 v[94:95], v[94:95], v[94:95]
	v_pk_mul_f32 v[96:97], v[96:97], v[96:97]
	v_pk_mul_f32 v[102:103], v[90:91], v[90:91]
	v_lshl_add_u64 v[98:99], v[98:99], 0, v[158:159]
	v_cvt_pk_bf16_f32 v90, v94, v95
	v_cvt_pk_bf16_f32 v91, v96, v97
	v_cvt_pk_bf16_f32 v92, v100, v101
	v_cvt_pk_bf16_f32 v93, v102, v103
	v_max_f32_e32 v82, 0, v82
	v_max_f32_e32 v83, 0, v83
	global_store_dwordx4 v[98:99], v[90:93], off
	s_nop 1
	v_pk_mul_f32 v[90:91], v[82:83], v[82:83]
	v_max_f32_e32 v86, 0, v86
	v_max_f32_e32 v87, 0, v87
	v_max_f32_e32 v88, 0, v88
	v_max_f32_e32 v89, 0, v89
	v_max_f32_e32 v82, 0, v84
	v_max_f32_e32 v83, 0, v85
	v_pk_mul_f32 v[86:87], v[86:87], v[86:87]
	v_pk_mul_f32 v[88:89], v[88:89], v[88:89]
	v_pk_mul_f32 v[92:93], v[82:83], v[82:83]
	v_cvt_pk_bf16_f32 v82, v86, v87
	v_cvt_pk_bf16_f32 v83, v88, v89
	v_cvt_pk_bf16_f32 v84, v90, v91
	v_cvt_pk_bf16_f32 v85, v92, v93
	global_store_dwordx4 v[98:99], v[82:85], off offset:256
	v_max_f32_e32 v74, 0, v74
	v_max_f32_e32 v75, 0, v75
	v_or_b32_e32 v82, 48, v154
	v_ashrrev_i32_e32 v83, 31, v82
	v_pk_mul_f32 v[84:85], v[74:75], v[74:75]
	v_lshlrev_b64 v[82:83], 13, v[82:83]
	v_max_f32_e32 v78, 0, v78
	v_max_f32_e32 v79, 0, v79
	v_max_f32_e32 v80, 0, v80
	v_max_f32_e32 v81, 0, v81
	v_max_f32_e32 v74, 0, v76
	v_max_f32_e32 v75, 0, v77
	v_lshl_add_u64 v[82:83], s[66:67], 0, v[82:83]
	v_pk_mul_f32 v[78:79], v[78:79], v[78:79]
	v_pk_mul_f32 v[80:81], v[80:81], v[80:81]
	v_pk_mul_f32 v[86:87], v[74:75], v[74:75]
	v_lshl_add_u64 v[82:83], v[82:83], 0, v[158:159]
	v_cvt_pk_bf16_f32 v74, v78, v79
	v_cvt_pk_bf16_f32 v75, v80, v81
	v_cvt_pk_bf16_f32 v76, v84, v85
	v_cvt_pk_bf16_f32 v77, v86, v87
	v_max_f32_e32 v66, 0, v66
	v_max_f32_e32 v67, 0, v67
	global_store_dwordx4 v[82:83], v[74:77], off
	s_nop 1
	v_pk_mul_f32 v[74:75], v[66:67], v[66:67]
	v_max_f32_e32 v70, 0, v70
	v_max_f32_e32 v71, 0, v71
	v_max_f32_e32 v72, 0, v72
	v_max_f32_e32 v73, 0, v73
	v_max_f32_e32 v66, 0, v68
	v_max_f32_e32 v67, 0, v69
	v_pk_mul_f32 v[70:71], v[70:71], v[70:71]
	v_pk_mul_f32 v[72:73], v[72:73], v[72:73]
	v_pk_mul_f32 v[76:77], v[66:67], v[66:67]
	v_cvt_pk_bf16_f32 v66, v70, v71
; DI unsigned pk_bf16(float a, float b) { f32x2 v = {a, b}; bf2_t r = __builtin_convertvector(v, bf2_t); return __builtin_bit_cast(unsigned, r); }
; #define PG8_BAR __builtin_amdgcn_s_barrier()
; template <class Epi, class Sched, bool ALIGN_EPI = false, bool SP2 = false>
; __device__ __forceinline__ void gemm_phase(PG8_LAS unsigned char* lds, const Gemm g, const Sched& S, const Epi& E) {
;     ...
;         if constexpr (!Epi::AFTER_DRAIN) { E(acc, cur, wr, wc, fr, fq); S.done(cur); }
;         if (!has_next) break;
; #pragma unroll
;         for (int a = 0; a < 2; ++a)
; #pragma unroll
;             for (int b = 0; b < 2; ++b)
; #pragma unroll
;                 for (int m = 0; m < 4; ++m)
; #pragma unroll
;                     for (int n = 0; n < 2; ++n) acc[a][b][m][n] = (f32x4){0.f, 0.f, 0.f, 0.f};
;         cur = nxt; cA = nA; cB = nB; ++ui;
;         if constexpr (ALIGN_EPI) { if (wr == 1) PG8_BAR; }
;     DI void operator()(const pg8::f32x4 (&acc)[2][2][4][2], const pg8::Unit& u, int wr, int wc, int fr, int fq) const {
;         const int row0 = u.pm * 256 + wr * 64 + fr, col0 = u.pn * 256 + wc * 32 + 8 * fq;
; #pragma unroll
;         for (int ai = 0; ai < 2; ++ai)
; #pragma unroll
;             for (int m = 0; m < 4; ++m) {
;                 const int row = row0 + ai * 128 + m * 16;
;                 bf16_t* rp = U + (size_t)row * 4096 + col0;
; #pragma unroll
;                 for (int bj = 0; bj < 2; ++bj) {
;                     float v[8];
; #pragma unroll
;                     for (int n = 0; n < 2; ++n)
; #pragma unroll
;                         for (int e = 0; e < 4; ++e) { const float t = fmaxf(acc[ai][bj][m][n][e], 0.f); v[4 * n + e] = t * t; }
;                     u32x4 w; w.x = pk_bf16(v[0], v[1]); w.y = pk_bf16(v[2], v[3]); w.z = pk_bf16(v[4], v[5]); w.w = pk_bf16(v[6], v[7]);
;                     *(u32x4*)(rp + bj * 128) = w;
;                 }
;             }
	v_cvt_pk_bf16_f32 v67, v72, v73
	v_cvt_pk_bf16_f32 v68, v74, v75
	v_cvt_pk_bf16_f32 v69, v76, v77
	v_max_f32_e32 v58, 0, v58
	v_max_f32_e32 v59, 0, v59
	global_store_dwordx4 v[82:83], v[66:69], off offset:256
	v_max_f32_e32 v62, 0, v62
	v_max_f32_e32 v63, 0, v63
	v_pk_mul_f32 v[68:69], v[58:59], v[58:59]
	v_pk_mul_f32 v[62:63], v[62:63], v[62:63]
	v_max_f32_e32 v64, 0, v64
	v_max_f32_e32 v65, 0, v65
	v_max_f32_e32 v58, 0, v60
	v_max_f32_e32 v59, 0, v61
	v_pk_mul_f32 v[64:65], v[64:65], v[64:65]
	v_pk_mul_f32 v[70:71], v[58:59], v[58:59]
	v_cvt_pk_bf16_f32 v58, v62, v63
	v_add_co_u32_e32 v62, vcc, s53, v146
	v_cvt_pk_bf16_f32 v59, v64, v65
	v_cvt_pk_bf16_f32 v60, v68, v69
	v_cvt_pk_bf16_f32 v61, v70, v71
	v_addc_co_u32_e32 v63, vcc, 0, v147, vcc
	v_max_f32_e32 v46, 0, v46
	v_max_f32_e32 v47, 0, v47
	global_store_dwordx4 v[62:63], v[58:61], off
	s_nop 1
	v_pk_mul_f32 v[58:59], v[46:47], v[46:47]
	v_max_f32_e32 v54, 0, v54
	v_max_f32_e32 v55, 0, v55
	v_max_f32_e32 v56, 0, v56
	v_max_f32_e32 v57, 0, v57
	v_max_f32_e32 v46, 0, v48
	v_max_f32_e32 v47, 0, v49
	v_pk_mul_f32 v[54:55], v[54:55], v[54:55]
	v_pk_mul_f32 v[56:57], v[56:57], v[56:57]
	v_pk_mul_f32 v[60:61], v[46:47], v[46:47]
	v_lshl_add_u64 v[66:67], v[146:147], 0, s[12:13]
	v_cvt_pk_bf16_f32 v46, v54, v55
	v_cvt_pk_bf16_f32 v47, v56, v57
	v_cvt_pk_bf16_f32 v48, v58, v59
	v_cvt_pk_bf16_f32 v49, v60, v61
	global_store_dwordx4 v[66:67], v[46:49], off offset:256
	v_max_f32_e32 v42, 0, v42
	v_max_f32_e32 v43, 0, v43
	v_max_f32_e32 v48, 0, v50
	v_max_f32_e32 v49, 0, v51
	v_max_f32_e32 v50, v52, v52
	v_max_f32_e32 v51, v53, v53
	v_pk_mul_f32 v[52:53], v[42:43], v[42:43]
	v_pk_mul_f32 v[48:49], v[48:49], v[48:49]
	v_max_f32_e32 v50, 0, v50
	v_max_f32_e32 v51, 0, v51
	v_max_f32_e32 v42, 0, v44
	v_max_f32_e32 v43, 0, v45
	v_pk_mul_f32 v[50:51], v[50:51], v[50:51]
	v_pk_mul_f32 v[54:55], v[42:43], v[42:43]
	v_cvt_pk_bf16_f32 v42, v48, v49
	v_add_co_u32_e32 v48, vcc, s54, v146
	v_cvt_pk_bf16_f32 v43, v50, v51
	v_cvt_pk_bf16_f32 v44, v52, v53
	v_cvt_pk_bf16_f32 v45, v54, v55
	v_addc_co_u32_e32 v49, vcc, 0, v147, vcc
	v_max_f32_e32 v30, 0, v30
	v_max_f32_e32 v31, 0, v31
	global_store_dwordx4 v[48:49], v[42:45], off
	s_nop 1
	v_pk_mul_f32 v[42:43], v[30:31], v[30:31]
	v_max_f32_e32 v38, 0, v38
	v_max_f32_e32 v39, 0, v39
	v_max_f32_e32 v40, 0, v40
	v_max_f32_e32 v41, 0, v41
	v_max_f32_e32 v30, 0, v32
	v_max_f32_e32 v31, 0, v33
	v_pk_mul_f32 v[38:39], v[38:39], v[38:39]
	v_pk_mul_f32 v[40:41], v[40:41], v[40:41]
	v_pk_mul_f32 v[44:45], v[30:31], v[30:31]
	v_lshl_add_u64 v[46:47], v[146:147], 0, s[14:15]
	v_cvt_pk_bf16_f32 v30, v38, v39
	v_cvt_pk_bf16_f32 v31, v40, v41
	v_cvt_pk_bf16_f32 v32, v42, v43
	v_cvt_pk_bf16_f32 v33, v44, v45
	global_store_dwordx4 v[46:47], v[30:33], off offset:256
	v_max_f32_e32 v26, 0, v26
	v_max_f32_e32 v27, 0, v27
	v_max_f32_e32 v32, 0, v34
	v_max_f32_e32 v33, 0, v35
	v_max_f32_e32 v34, v36, v36
	v_max_f32_e32 v35, v37, v37
	v_pk_mul_f32 v[36:37], v[26:27], v[26:27]
	v_pk_mul_f32 v[32:33], v[32:33], v[32:33]
	v_max_f32_e32 v34, 0, v34
	v_max_f32_e32 v35, 0, v35
	v_max_f32_e32 v26, 0, v28
	v_max_f32_e32 v27, 0, v29
	v_pk_mul_f32 v[34:35], v[34:35], v[34:35]
	v_pk_mul_f32 v[38:39], v[26:27], v[26:27]
	v_cvt_pk_bf16_f32 v26, v32, v33
	v_add_co_u32_e32 v32, vcc, s55, v146
	v_cvt_pk_bf16_f32 v27, v34, v35
	v_cvt_pk_bf16_f32 v28, v36, v37
	v_cvt_pk_bf16_f32 v29, v38, v39
	v_addc_co_u32_e32 v33, vcc, 0, v147, vcc
	v_max_f32_e32 v14, 0, v14
	v_max_f32_e32 v15, 0, v15
	global_store_dwordx4 v[32:33], v[26:29], off
	s_nop 1
	v_pk_mul_f32 v[26:27], v[14:15], v[14:15]
	v_max_f32_e32 v22, 0, v22
	v_max_f32_e32 v23, 0, v23
	v_max_f32_e32 v24, 0, v24
	v_max_f32_e32 v25, 0, v25
	v_max_f32_e32 v14, 0, v16
	v_max_f32_e32 v15, 0, v17
	v_pk_mul_f32 v[22:23], v[22:23], v[22:23]
	v_pk_mul_f32 v[24:25], v[24:25], v[24:25]
	v_pk_mul_f32 v[28:29], v[14:15], v[14:15]
	v_lshl_add_u64 v[30:31], v[146:147], 0, s[16:17]
	v_cvt_pk_bf16_f32 v14, v22, v23
	v_cvt_pk_bf16_f32 v15, v24, v25
	v_cvt_pk_bf16_f32 v16, v26, v27
	v_cvt_pk_bf16_f32 v17, v28, v29
	global_store_dwordx4 v[30:31], v[14:17], off offset:256
	v_max_f32_e32 v10, 0, v10
	v_max_f32_e32 v11, 0, v11
	v_max_f32_e32 v16, 0, v18
	v_max_f32_e32 v17, 0, v19
	v_max_f32_e32 v18, v20, v20
	v_max_f32_e32 v19, v21, v21
	v_pk_mul_f32 v[20:21], v[10:11], v[10:11]
	v_pk_mul_f32 v[16:17], v[16:17], v[16:17]
	v_max_f32_e32 v18, 0, v18
	v_max_f32_e32 v19, 0, v19
	v_max_f32_e32 v10, 0, v12
	v_max_f32_e32 v11, 0, v13
	v_pk_mul_f32 v[18:19], v[18:19], v[18:19]
	v_pk_mul_f32 v[22:23], v[10:11], v[10:11]
	v_cvt_pk_bf16_f32 v10, v16, v17
	v_add_co_u32_e32 v16, vcc, s56, v146
	v_cvt_pk_bf16_f32 v11, v18, v19
	v_cvt_pk_bf16_f32 v12, v20, v21
	v_cvt_pk_bf16_f32 v13, v22, v23
	v_addc_co_u32_e32 v17, vcc, 0, v147, vcc
	v_max_f32_e32 v2, 0, v2
	v_max_f32_e32 v3, 0, v3
	global_store_dwordx4 v[16:17], v[10:13], off
	s_nop 1
	v_pk_mul_f32 v[10:11], v[2:3], v[2:3]
	v_max_f32_e32 v6, 0, v6
	v_max_f32_e32 v7, 0, v7
	v_max_f32_e32 v8, 0, v8
	v_max_f32_e32 v9, 0, v9
	v_max_f32_e32 v2, 0, v4
	v_max_f32_e32 v3, 0, v5
	v_pk_mul_f32 v[6:7], v[6:7], v[6:7]
	v_pk_mul_f32 v[8:9], v[8:9], v[8:9]
	v_pk_mul_f32 v[12:13], v[2:3], v[2:3]
	v_lshl_add_u64 v[14:15], v[146:147], 0, s[18:19]
	v_cvt_pk_bf16_f32 v2, v6, v7
	v_cvt_pk_bf16_f32 v3, v8, v9
	v_cvt_pk_bf16_f32 v4, v10, v11
	v_cvt_pk_bf16_f32 v5, v12, v13
	s_andn2_b64 vcc, exec, s[2:3]
	s_mov_b64 s[2:3], -1
	global_store_dwordx4 v[14:15], v[2:5], off offset:256
	s_cbranch_vccnz .LBB0_1464
	s_andn2_b64 vcc, exec, s[6:7]
	s_cbranch_vccnz .LBB0_1463
	s_barrier
	s_branch .LBB0_1463

; #define MFMA32(a, b, c) __builtin_amdgcn_mfma_f32_32x32x16_bf16((a), (b), (c), 0, 0, 0)
; DI float xhalf_sum(float v) { const auto r = __builtin_amdgcn_permlane32_swap(__float_as_uint(v), __float_as_uint(v), false, false); return __uint_as_float(r[0]) + __uint_as_float(r[1]); }
; DI void phase_index(const Params& p, unsigned char* lds) {
;     ...
;         auto mma = [&](f32x16& s, unsigned off) {
; #pragma unroll
;             for (int i = 0; i < 16; ++i) s[i] = 0.f;
; #pragma unroll
;             for (int ks = 0; ks < 4; ++ks) { const bf16x8 kf = *(const bf16x8*)(lds + off + ks * 32); s = MFMA32(qf[ks], kf, s); }
;         };
;         auto proc = [&](auto PASSC, auto DIAGC, const f32x16& s, int k0, int kb) {
;             constexpr int PASS = decltype(PASSC)::value; constexpr bool DIAG = decltype(DIAGC)::value != 0;
;             f32x4 tot;
; #pragma unroll
;             for (int q = 0; q < 4; ++q) {
;                 float pr = 0.f;
; #pragma unroll
;                 for (int e = 0; e < 4; ++e) pr += wq[q][e] * fmaxf(s[4 * q + e], 0.f);
;                 tot[q] = xhalf_sum(pr);
;             }
;             const int key = k0 + 32 * kb + r32;
; #pragma unroll
;             for (int qq = 0; qq < 2; ++qq) {
;                 const float t_lo = tot[qq], t_hi = tot[2 + qq];
;                 const float sc = ((lane & 32) ? t_hi : t_lo) + 0.0f;
;                 const unsigned ub = __float_as_uint(sc);
;                 const unsigned uk = ub ^ ((unsigned)((int)ub >> 31) | 0x80000000u);
;                 const bool valid = DIAG ? (key <= tq0 + qq) : true;
;                 if (PASS == 0) {
;                     if (valid) { const unsigned a = (uk >> 21) & 0x7feu; atomicAdd((unsigned*)(lds + hbase0 + qq * 2048 + (a & ~3u)), 1u << ((a & 2u) << 3)); }
.LBB0_2567:
	s_bitcmp1_b32 s28, 0
	s_cselect_b32 s34, 0x9000, 0
	v_add_u32_e32 v106, s34, v154
	ds_read_b128 v[2:5], v106
	ds_read_b128 v[6:9], v106 offset:32
	s_cmp_lg_u32 s0, 0
	s_cselect_b64 s[28:29], -1, 0
	s_and_b64 vcc, exec, s[28:29]
	s_waitcnt lgkmcnt(1)
	v_mfma_f32_32x32x16_bf16 v[18:33], v[42:45], v[2:5], 0
	ds_read_b128 v[2:5], v106 offset:64
	ds_read_b128 v[102:105], v106 offset:96
	s_waitcnt lgkmcnt(2)
	v_mfma_f32_32x32x16_bf16 v[18:33], v[34:37], v[6:9], v[18:33]
	s_waitcnt lgkmcnt(1)
	v_mfma_f32_32x32x16_bf16 v[18:33], v[38:41], v[2:5], v[18:33]
	ds_read_b128 v[2:5], v106 offset:4608
	ds_read_b128 v[108:111], v106 offset:4640
	s_waitcnt lgkmcnt(2)
	v_mfma_f32_32x32x16_bf16 v[18:33], v[46:49], v[102:105], v[18:33]
	s_waitcnt lgkmcnt(1)
	v_mfma_f32_32x32x16_bf16 v[2:17], v[42:45], v[2:5], 0
	s_nop 9
	v_max_f32_e32 v21, v21, v21
	v_max_f32_e32 v22, v22, v22
	v_max_f32_e32 v20, v20, v20
	v_max_f32_e32 v23, v23, v23
	v_max_f32_e32 v18, 0, v18
	v_max_f32_e32 v103, 0, v21
	v_max_f32_e32 v21, 0, v22
	v_max_f32_e32 v24, v24, v24
	v_max_f32_e32 v102, 0, v20
	v_max_f32_e32 v22, 0, v23
	v_fma_f32 v20, v50, v18, 0
	v_fma_f32 v18, v54, v21, 0
	s_waitcnt lgkmcnt(0)
	v_mfma_f32_32x32x16_bf16 v[2:17], v[34:37], v[108:111], v[2:17]
	v_max_f32_e32 v25, v25, v25
	v_max_f32_e32 v26, v26, v26
	v_max_f32_e32 v23, 0, v24
	v_fmac_f32_e32 v18, v55, v22
	v_max_f32_e32 v24, 0, v25
	v_max_f32_e32 v25, 0, v26
	v_fmac_f32_e32 v18, v56, v23
	v_fma_f32 v21, v58, v25, 0
	v_fmac_f32_e32 v18, v57, v24
	ds_read_b128 v[22:25], v106 offset:4672
	v_max_f32_e32 v27, v27, v27
	v_max_f32_e32 v28, v28, v28
	v_max_f32_e32 v19, 0, v19
	v_max_f32_e32 v26, 0, v27
	v_max_f32_e32 v27, 0, v28
	v_fmac_f32_e32 v20, v51, v19
	v_fmac_f32_e32 v21, v59, v26
	v_fmac_f32_e32 v21, v60, v27
	v_max_f32_e32 v19, 0, v29
	v_max_f32_e32 v26, v31, v31
	v_fmac_f32_e32 v21, v61, v19
	v_max_f32_e32 v19, v30, v30
	v_max_f32_e32 v30, 0, v26
	ds_read_b128 v[26:29], v106 offset:4704
	s_waitcnt lgkmcnt(1)
	v_mfma_f32_32x32x16_bf16 v[2:17], v[38:41], v[22:25], v[2:17]
	v_max_f32_e32 v19, 0, v19
	v_fma_f32 v19, v62, v19, 0
	v_fmac_f32_e32 v19, v63, v30
	v_max_f32_e32 v22, 0, v32
	v_fmac_f32_e32 v19, v64, v22
	s_waitcnt lgkmcnt(0)
	v_mfma_f32_32x32x16_bf16 v[2:17], v[46:49], v[26:29], v[2:17]
	v_fmac_f32_e32 v20, v52, v102
	v_max_f32_e32 v22, 0, v33
	v_fmac_f32_e32 v20, v53, v103
	v_fmac_f32_e32 v19, v65, v22
	s_cbranch_vccz .LBB0_2575
	v_mov_b32_e32 v22, v20
	v_mov_b32_e32 v23, v20
	s_nop 1
	v_permlane32_swap_b32_e32 v22, v23
	v_add_f32_e32 v22, v22, v23
	v_mov_b32_e32 v23, v18
	v_mov_b32_e32 v24, v18
	s_nop 1
	v_permlane32_swap_b32_e32 v23, v24
	v_add_f32_e32 v23, v23, v24
	v_mov_b32_e32 v24, v21
	v_mov_b32_e32 v25, v21
	s_nop 1
	v_permlane32_swap_b32_e32 v24, v25
	v_add_f32_e32 v24, v24, v25
	v_cndmask_b32_e64 v22, v24, v22, s[4:5]
	v_add_f32_e32 v22, 0, v22
	v_ashrrev_i32_e32 v24, 31, v22
	v_bitop3_b32 v22, v24, v22, s82 bitop3:0x36
	v_lshrrev_b32_e32 v24, 21, v22
	v_lshrrev_b32_e32 v22, 18, v22
	v_and_b32_e32 v24, 0x7fc, v24
	v_and_b32_e32 v22, 16, v22
	v_add_u32_e32 v24, v123, v24
	v_lshlrev_b32_e64 v22, v22, 1
	ds_add_u32 v24, v22
	v_mov_b32_e32 v25, v19
	v_mov_b32_e32 v26, v19
	s_nop 1
	v_permlane32_swap_b32_e32 v25, v26
	v_add_f32_e32 v22, v25, v26
	v_cndmask_b32_e64 v22, v22, v23, s[4:5]
	s_mov_b64 s[30:31], -1
	s_cbranch_execz .LBB0_2576
	s_and_saveexec_b64 s[50:51], s[30:31]
	s_cbranch_execz .LBB0_2571

; DI float xhalf_sum(float v) { const auto r = __builtin_amdgcn_permlane32_swap(__float_as_uint(v), __float_as_uint(v), false, false); return __uint_as_float(r[0]) + __uint_as_float(r[1]); }
; DI void phase_index(const Params& p, unsigned char* lds) {
;     ...
;         auto proc = [&](auto PASSC, auto DIAGC, const f32x16& s, int k0, int kb) {
;             constexpr int PASS = decltype(PASSC)::value; constexpr bool DIAG = decltype(DIAGC)::value != 0;
;             f32x4 tot;
; #pragma unroll
;             for (int q = 0; q < 4; ++q) {
;                 float pr = 0.f;
; #pragma unroll
;                 for (int e = 0; e < 4; ++e) pr += wq[q][e] * fmaxf(s[4 * q + e], 0.f);
;                 tot[q] = xhalf_sum(pr);
;             }
;             const int key = k0 + 32 * kb + r32;
; #pragma unroll
;             for (int qq = 0; qq < 2; ++qq) {
;                 const float t_lo = tot[qq], t_hi = tot[2 + qq];
;                 const float sc = ((lane & 32) ? t_hi : t_lo) + 0.0f;
;                 const unsigned ub = __float_as_uint(sc);
;                 const unsigned uk = ub ^ ((unsigned)((int)ub >> 31) | 0x80000000u);
;                 const bool valid = DIAG ? (key <= tq0 + qq) : true;
;                 if (PASS == 0) {
;                     if (valid) { const unsigned a = (uk >> 21) & 0x7feu; atomicAdd((unsigned*)(lds + hbase0 + qq * 2048 + (a & ~3u)), 1u << ((a & 2u) << 3)); }
.LBB0_2571:
	s_or_b64 exec, exec, s[50:51]
	v_max_f32_e32 v2, 0, v2
	v_fma_f32 v2, v50, v2, 0
	v_max_f32_e32 v3, 0, v3
	v_fmac_f32_e32 v2, v51, v3
	v_max_f32_e32 v3, 0, v4
	v_fmac_f32_e32 v2, v52, v3
	v_max_f32_e32 v3, 0, v5
	v_fmac_f32_e32 v2, v53, v3
	s_and_b64 vcc, exec, s[28:29]
	v_max_f32_e32 v21, v6, v6
	v_max_f32_e32 v20, v7, v7
	v_max_f32_e32 v19, v8, v8
	v_max_f32_e32 v18, v9, v9
	v_max_f32_e32 v10, v10, v10
	v_max_f32_e32 v9, v11, v11
	v_max_f32_e32 v8, v12, v12
	v_max_f32_e32 v7, v13, v13
	v_max_f32_e32 v6, v14, v14
	v_max_f32_e32 v5, v15, v15
	v_max_f32_e32 v4, v16, v16
	v_max_f32_e32 v3, v17, v17
	s_cbranch_vccz .LBB0_2581
	v_mov_b32_e32 v11, v2
	v_mov_b32_e32 v12, v2
	s_nop 1
	v_permlane32_swap_b32_e32 v11, v12
	v_add_f32_e32 v11, v11, v12
	v_max_f32_e32 v12, 0, v21
	v_max_f32_e32 v13, 0, v20
	v_pk_mul_f32 v[12:13], v[54:55], v[12:13]
	s_nop 0
	v_add_f32_e32 v12, 0, v12
	v_add_f32_e32 v14, v13, v12
	v_max_f32_e32 v12, 0, v19
	v_max_f32_e32 v13, 0, v18
	v_pk_mul_f32 v[12:13], v[56:57], v[12:13]
	s_mov_b64 s[28:29], -1
	v_add_f32_e32 v12, v12, v14
	v_add_f32_e32 v12, v13, v12
	v_mov_b32_e32 v13, v12
	s_nop 1
	v_permlane32_swap_b32_e32 v12, v13
	v_add_f32_e32 v14, v12, v13
	v_max_f32_e32 v12, 0, v10
	v_fma_f32 v12, v58, v12, 0
	v_max_f32_e32 v13, 0, v9
	v_fmac_f32_e32 v12, v59, v13
	v_max_f32_e32 v13, 0, v8
	v_fmac_f32_e32 v12, v60, v13
	v_max_f32_e32 v13, 0, v7
	v_fmac_f32_e32 v12, v61, v13
	v_mov_b32_e32 v13, v12
	s_nop 1
	v_permlane32_swap_b32_e32 v12, v13
	v_add_f32_e32 v15, v12, v13
	v_cndmask_b32_e64 v11, v15, v11, s[4:5]
	v_max_f32_e32 v12, 0, v6
	v_max_f32_e32 v13, 0, v5
	v_add_f32_e32 v11, 0, v11
	v_pk_mul_f32 v[12:13], v[62:63], v[12:13]
	v_ashrrev_i32_e32 v15, 31, v11
	v_add_f32_e32 v12, 0, v12
	v_bitop3_b32 v11, v15, v11, s82 bitop3:0x36
	v_add_f32_e32 v16, v13, v12
	v_max_f32_e32 v12, 0, v4
	v_max_f32_e32 v13, 0, v3
	v_lshrrev_b32_e32 v15, 21, v11
	v_lshrrev_b32_e32 v11, 18, v11
	v_pk_mul_f32 v[12:13], v[64:65], v[12:13]
	v_and_b32_e32 v15, 0x7fc, v15
	v_and_b32_e32 v11, 16, v11
	v_add_f32_e32 v12, v12, v16
	v_add_u32_e32 v15, v123, v15
	v_lshlrev_b32_e64 v11, v11, 1
	v_add_f32_e32 v12, v13, v12
	ds_add_u32 v15, v11
	v_mov_b32_e32 v13, v12
	s_nop 1
	v_permlane32_swap_b32_e32 v12, v13
	v_add_f32_e32 v11, v12, v13
	v_cndmask_b32_e64 v13, v11, v14, s[4:5]
	s_cbranch_execz .LBB0_2582
	s_and_saveexec_b64 s[30:31], s[28:29]
	s_cbranch_execnz .LBB0_2587

; #define MFMA32(a, b, c) __builtin_amdgcn_mfma_f32_32x32x16_bf16((a), (b), (c), 0, 0, 0)
; DI float xhalf_sum(float v) { const auto r = __builtin_amdgcn_permlane32_swap(__float_as_uint(v), __float_as_uint(v), false, false); return __uint_as_float(r[0]) + __uint_as_float(r[1]); }
; DI void phase_index(const Params& p, unsigned char* lds) {
;     ...
;         auto mma = [&](f32x16& s, unsigned off) {
; #pragma unroll
;             for (int i = 0; i < 16; ++i) s[i] = 0.f;
; #pragma unroll
;             for (int ks = 0; ks < 4; ++ks) { const bf16x8 kf = *(const bf16x8*)(lds + off + ks * 32); s = MFMA32(qf[ks], kf, s); }
;         };
;         auto proc = [&](auto PASSC, auto DIAGC, const f32x16& s, int k0, int kb) {
;             constexpr int PASS = decltype(PASSC)::value; constexpr bool DIAG = decltype(DIAGC)::value != 0;
;             f32x4 tot;
; #pragma unroll
;             for (int q = 0; q < 4; ++q) {
;                 float pr = 0.f;
; #pragma unroll
;                 for (int e = 0; e < 4; ++e) pr += wq[q][e] * fmaxf(s[4 * q + e], 0.f);
;                 tot[q] = xhalf_sum(pr);
.LBB0_2635:
	v_add_u32_e32 v168, s1, v163
	v_add_u32_e32 v18, 0x11200, v168
	ds_read_b128 v[18:21], v18
	v_add_u32_e32 v22, 0x11220, v168
	ds_read_b128 v[172:175], v22
	v_add_u32_e32 v177, 0x11240, v168
	s_waitcnt lgkmcnt(1)
	v_mfma_f32_32x32x16_bf16 v[18:33], v[42:45], v[18:21], 0
	v_max_f32_e32 v170, v4, v4
	v_max_f32_e32 v180, v6, v6
	v_max_f32_e32 v181, v7, v7
	v_max_f32_e32 v167, 0, v2
	v_max_f32_e32 v182, 0, v170
	v_max_f32_e32 v170, 0, v180
	v_fma_f32 v170, v54, v170, 0
	s_waitcnt lgkmcnt(0)
	v_mfma_f32_32x32x16_bf16 v[18:33], v[34:37], v[172:175], v[18:33]
	ds_read_b128 v[172:175], v177
	v_max_f32_e32 v176, v5, v5
	v_add_u32_e32 v178, 0x11260, v168
	v_max_f32_e32 v183, 0, v176
	ds_read_b128 v[176:179], v178
	v_max_f32_e32 v169, 0, v3
	s_waitcnt lgkmcnt(1)
	v_mfma_f32_32x32x16_bf16 v[18:33], v[38:41], v[172:175], v[18:33]
	v_max_f32_e32 v172, 0, v181
	v_fma_f32 v173, v50, v167, 0
	v_fmac_f32_e32 v170, v55, v172
	v_max_f32_e32 v167, 0, v8
	v_fmac_f32_e32 v170, v56, v167
	v_max_f32_e32 v167, 0, v9
	v_fmac_f32_e32 v170, v57, v167
	v_max_f32_e32 v167, 0, v10
	v_fma_f32 v174, v58, v167, 0
	v_max_f32_e32 v167, 0, v11
	v_fmac_f32_e32 v174, v59, v167
	v_max_f32_e32 v167, 0, v12
	v_fmac_f32_e32 v174, v60, v167
	v_max_f32_e32 v167, 0, v13
	v_fmac_f32_e32 v174, v61, v167
	s_waitcnt lgkmcnt(0)
	v_mfma_f32_32x32x16_bf16 v[18:33], v[46:49], v[176:179], v[18:33]
	v_max_f32_e32 v167, 0, v14
	v_fma_f32 v172, v62, v167, 0
	v_max_f32_e32 v167, 0, v15
	v_fmac_f32_e32 v172, v63, v167
	v_max_f32_e32 v167, 0, v16
	s_cmp_lg_u32 s52, s55
	v_fmac_f32_e32 v173, v51, v169
	v_fmac_f32_e32 v172, v64, v167
	s_cselect_b64 s[28:29], -1, 0
	v_fmac_f32_e32 v173, v52, v182
	v_max_f32_e32 v167, 0, v17
	v_fmac_f32_e32 v173, v53, v183
	v_fmac_f32_e32 v172, v65, v167
	s_mov_b64 s[30:31], -1
	s_and_b64 vcc, exec, s[28:29]
	s_cbranch_vccnz .LBB0_2669
	s_and_b64 vcc, exec, s[30:31]
	s_cbranch_vccnz .LBB0_2682

; DI float xhalf_sum(float v) { const auto r = __builtin_amdgcn_permlane32_swap(__float_as_uint(v), __float_as_uint(v), false, false); return __uint_as_float(r[0]) + __uint_as_float(r[1]); }
; DI void phase_index(const Params& p, unsigned char* lds) {
;     ...
;         auto proc = [&](auto PASSC, auto DIAGC, const f32x16& s, int k0, int kb) {
;             constexpr int PASS = decltype(PASSC)::value; constexpr bool DIAG = decltype(DIAGC)::value != 0;
;             f32x4 tot;
; #pragma unroll
;             for (int q = 0; q < 4; ++q) {
;                 float pr = 0.f;
; #pragma unroll
;                 for (int e = 0; e < 4; ++e) pr += wq[q][e] * fmaxf(s[4 * q + e], 0.f);
;                 tot[q] = xhalf_sum(pr);
;             }
;             const int key = k0 + 32 * kb + r32;
; #pragma unroll
;             for (int qq = 0; qq < 2; ++qq) {
;                 const float t_lo = tot[qq], t_hi = tot[2 + qq];
;                 const float sc = ((lane & 32) ? t_hi : t_lo) + 0.0f;
;                 const unsigned ub = __float_as_uint(sc);
;                 const unsigned uk = ub ^ ((unsigned)((int)ub >> 31) | 0x80000000u);
;                 const bool valid = DIAG ? (key <= tq0 + qq) : true;
;                 if (PASS == 0) {
;                     if (valid) { const unsigned a = (uk >> 21) & 0x7feu; atomicAdd((unsigned*)(lds + hbase0 + qq * 2048 + (a & ~3u)), 1u << ((a & 2u) << 3)); }
;                 } else if (PASS == 1) {
;                     if (valid && (int)(uk >> 22) == b1v[qq]) { const unsigned a = (uk >> 11) & 0x7feu; atomicAdd((unsigned*)(lds + hbase0 + qq * 2048 + (a & ~3u)), 1u << ((a & 2u) << 3)); }
;                 } else if (PASS == 3) {
;                     if (valid) {
;                         const int k10 = (int)(uk >> 22), d = k10 - b1v[qq];
;                         if (k10 > hiv[qq]) cntA[qq] += 1;
;                         else if (d >= 0) {
;                             const unsigned bin = ((unsigned)d << sbv[qq]) | ((uk >> (22 - sbv[qq])) & ((1u << sbv[qq]) - 1u));
;                             const unsigned a = bin << 1;
;                             atomicAdd((unsigned*)(lds + hbase0 + qq * 2048 + (a & ~3u)), 1u << ((a & 2u) << 3));
;                         }
;                     }
.LBB0_2639:
	v_max_f32_e32 v18, 0, v18
	v_fma_f32 v168, v50, v18, 0
	v_max_f32_e32 v18, 0, v19
	v_fmac_f32_e32 v168, v51, v18
	v_max_f32_e32 v18, 0, v20
	v_fmac_f32_e32 v168, v52, v18
	v_max_f32_e32 v18, 0, v21
	v_fmac_f32_e32 v168, v53, v18
	v_max_f32_e32 v18, 0, v22
	v_fma_f32 v18, v54, v18, 0
	v_max_f32_e32 v19, 0, v23
	v_fmac_f32_e32 v18, v55, v19
	v_max_f32_e32 v19, 0, v24
	v_fmac_f32_e32 v18, v56, v19
	v_max_f32_e32 v19, 0, v25
	v_fmac_f32_e32 v18, v57, v19
	v_max_f32_e32 v19, 0, v26
	v_fma_f32 v20, v58, v19, 0
	v_max_f32_e32 v19, 0, v27
	v_fmac_f32_e32 v20, v59, v19
	v_max_f32_e32 v19, 0, v28
	v_fmac_f32_e32 v20, v60, v19
	v_max_f32_e32 v19, 0, v29
	v_fmac_f32_e32 v20, v61, v19
	v_max_f32_e32 v19, 0, v30
	v_fma_f32 v19, v62, v19, 0
	v_max_f32_e32 v21, 0, v31
	v_fmac_f32_e32 v19, v63, v21
	v_max_f32_e32 v21, 0, v32
	v_fmac_f32_e32 v19, v64, v21
	v_max_f32_e32 v21, 0, v33
	v_fmac_f32_e32 v19, v65, v21
	s_mov_b64 s[30:31], -1
	s_and_b64 vcc, exec, s[28:29]
	s_cbranch_vccz .LBB0_2653
	v_mov_b32_e32 v21, v168
	v_mov_b32_e32 v22, v168
	v_mov_b32_e32 v23, v20
	v_mov_b32_e32 v24, v20
	v_permlane32_swap_b32_e32 v21, v22
	s_nop 0
	v_permlane32_swap_b32_e32 v23, v24
	v_add_f32_e32 v25, v21, v22
	v_add_f32_e32 v26, v23, v24
	v_cndmask_b32_e64 v25, v26, v25, s[4:5]
	v_add_f32_e32 v25, 0, v25
	v_ashrrev_i32_e32 v26, 31, v25
	v_bitop3_b32 v25, v26, v25, s82 bitop3:0x36
	v_mov_b32_e32 v21, v18
	v_mov_b32_e32 v22, v18
	v_mov_b32_e32 v23, v19
	v_mov_b32_e32 v24, v19
	v_lshrrev_b32_e32 v26, 22, v25
	v_permlane32_swap_b32_e32 v21, v22
	v_permlane32_swap_b32_e32 v23, v24
	v_cmp_le_i32_e32 vcc, v26, v101
	s_and_saveexec_b64 s[28:29], vcc
	s_xor_b64 s[28:29], exec, s[28:29]
	s_cbranch_execz .LBB0_2644
	v_sub_u32_e32 v26, v26, v100
	v_cmp_lt_i32_e32 vcc, -1, v26
	s_and_saveexec_b64 s[30:31], vcc
	s_cbranch_execz .LBB0_2643
	v_lshrrev_b32_e32 v25, v113, v25
	v_and_b32_e32 v25, v25, v114
	v_lshl_or_b32 v25, v26, v111, v25
	v_lshlrev_b32_e32 v26, 1, v25
	v_and_b32_e32 v26, -4, v26
	v_lshlrev_b32_e32 v25, 4, v25
	v_add_u32_e32 v26, v123, v26
	v_lshlrev_b32_e64 v25, v25, 1
	ds_add_u32 v26, v25

; #define MFMA32(a, b, c) __builtin_amdgcn_mfma_f32_32x32x16_bf16((a), (b), (c), 0, 0, 0)
; DI float xhalf_sum(float v) { const auto r = __builtin_amdgcn_permlane32_swap(__float_as_uint(v), __float_as_uint(v), false, false); return __uint_as_float(r[0]) + __uint_as_float(r[1]); }
; DI void phase_index(const Params& p, unsigned char* lds) {
;     ...
;         auto mma = [&](f32x16& s, unsigned off) {
; #pragma unroll
;             for (int i = 0; i < 16; ++i) s[i] = 0.f;
; #pragma unroll
;             for (int ks = 0; ks < 4; ++ks) { const bf16x8 kf = *(const bf16x8*)(lds + off + ks * 32); s = MFMA32(qf[ks], kf, s); }
;         };
;         auto proc = [&](auto PASSC, auto DIAGC, const f32x16& s, int k0, int kb) {
;             constexpr int PASS = decltype(PASSC)::value; constexpr bool DIAG = decltype(DIAGC)::value != 0;
;             f32x4 tot;
; #pragma unroll
;             for (int q = 0; q < 4; ++q) {
;                 float pr = 0.f;
; #pragma unroll
;                 for (int e = 0; e < 4; ++e) pr += wq[q][e] * fmaxf(s[4 * q + e], 0.f);
;                 tot[q] = xhalf_sum(pr);
;             }
;             const int key = k0 + 32 * kb + r32;
; #pragma unroll
;             for (int qq = 0; qq < 2; ++qq) {
;                 const float t_lo = tot[qq], t_hi = tot[2 + qq];
;                 const float sc = ((lane & 32) ? t_hi : t_lo) + 0.0f;
;                 const unsigned ub = __float_as_uint(sc);
;                 const unsigned uk = ub ^ ((unsigned)((int)ub >> 31) | 0x80000000u);
;                 const bool valid = DIAG ? (key <= tq0 + qq) : true;
;                 if (PASS == 0) {
;                     if (valid) { const unsigned a = (uk >> 21) & 0x7feu; atomicAdd((unsigned*)(lds + hbase0 + qq * 2048 + (a & ~3u)), 1u << ((a & 2u) << 3)); }
.LBB0_2966:
	ds_read_b128 v[18:21], v100
	ds_read_b128 v[108:111], v100 offset:32
	ds_read_b128 v[162:165], v100 offset:64
	ds_read_b128 v[166:169], v100 offset:96
	s_nop 0
	s_waitcnt lgkmcnt(3)
	v_mfma_f32_32x32x16_bf16 v[18:33], v[42:45], v[18:21], 0
	v_max_f32_e32 v102, 0, v2
	v_fma_f32 v102, v50, v102, 0
	v_max_f32_e32 v103, 0, v3
	v_fmac_f32_e32 v102, v51, v103
	v_max_f32_e32 v103, 0, v4
	s_waitcnt lgkmcnt(2)
	v_mfma_f32_32x32x16_bf16 v[18:33], v[34:37], v[108:111], v[18:33]
	s_cmp_lg_u32 s0, s53
	v_fmac_f32_e32 v102, v52, v103
	s_cselect_b64 s[30:31], -1, 0
	v_max_f32_e32 v103, 0, v5
	v_fmac_f32_e32 v102, v53, v103
	s_and_b64 vcc, exec, s[30:31]
	s_waitcnt lgkmcnt(1)
	v_mfma_f32_32x32x16_bf16 v[18:33], v[38:41], v[162:165], v[18:33]
	v_max_f32_e32 v114, v6, v6
	v_max_f32_e32 v115, v7, v7
	v_max_f32_e32 v113, v8, v8
	v_max_f32_e32 v112, v9, v9
	v_max_f32_e32 v111, v10, v10
	v_max_f32_e32 v110, v11, v11
	v_max_f32_e32 v109, v12, v12
	s_waitcnt lgkmcnt(0)
	v_mfma_f32_32x32x16_bf16 v[18:33], v[46:49], v[166:169], v[18:33]
	v_max_f32_e32 v108, v13, v13
	v_max_f32_e32 v106, v14, v14
	v_max_f32_e32 v105, v15, v15
	v_max_f32_e32 v104, v16, v16
	v_max_f32_e32 v103, v17, v17
	s_cbranch_vccz .LBB0_2968
	v_mov_b32_e32 v116, v102
	v_mov_b32_e32 v117, v102
	s_nop 1
	v_permlane32_swap_b32_e32 v116, v117
	v_add_f32_e32 v161, v116, v117
	v_max_f32_e32 v116, 0, v114
	v_max_f32_e32 v117, 0, v115
	v_pk_mul_f32 v[116:117], v[54:55], v[116:117]
	s_nop 0
	v_add_f32_e32 v116, 0, v116
	v_add_f32_e32 v162, v117, v116
	v_max_f32_e32 v116, 0, v113
	v_max_f32_e32 v117, 0, v112
	v_pk_mul_f32 v[116:117], v[56:57], v[116:117]
	s_mov_b64 s[38:39], -1
	v_add_f32_e32 v116, v116, v162
	v_add_f32_e32 v116, v117, v116
	v_mov_b32_e32 v117, v116
	s_nop 1
	v_permlane32_swap_b32_e32 v116, v117
	v_add_f32_e32 v162, v116, v117
	v_max_f32_e32 v116, 0, v111
	v_fma_f32 v116, v58, v116, 0
	v_max_f32_e32 v117, 0, v110
	v_fmac_f32_e32 v116, v59, v117
	v_max_f32_e32 v117, 0, v109
	v_fmac_f32_e32 v116, v60, v117
	v_max_f32_e32 v117, 0, v108
	v_fmac_f32_e32 v116, v61, v117
	v_mov_b32_e32 v117, v116
	s_nop 1
	v_permlane32_swap_b32_e32 v116, v117
	v_add_f32_e32 v163, v116, v117
	v_cndmask_b32_e64 v161, v163, v161, s[4:5]
	v_max_f32_e32 v116, 0, v106
	v_max_f32_e32 v117, 0, v105
	v_add_f32_e32 v161, 0, v161
	v_pk_mul_f32 v[116:117], v[62:63], v[116:117]
	v_ashrrev_i32_e32 v163, 31, v161
	v_add_f32_e32 v116, 0, v116
	v_bitop3_b32 v161, v163, v161, s82 bitop3:0x36
	v_add_f32_e32 v164, v117, v116
	v_max_f32_e32 v116, 0, v104
	v_max_f32_e32 v117, 0, v103
	v_lshrrev_b32_e32 v163, 21, v161
	v_lshrrev_b32_e32 v161, 18, v161
	v_pk_mul_f32 v[116:117], v[64:65], v[116:117]
	v_and_b32_e32 v163, 0x7fc, v163
	v_and_b32_e32 v161, 16, v161
	v_add_f32_e32 v116, v116, v164
	v_add_u32_e32 v163, v123, v163
	v_lshlrev_b32_e64 v161, v161, 1
	v_add_f32_e32 v116, v117, v116
	ds_add_u32 v163, v161
	v_mov_b32_e32 v117, v116
	s_nop 1
	v_permlane32_swap_b32_e32 v116, v117
	v_add_f32_e32 v116, v116, v117
	v_cndmask_b32_e64 v116, v116, v162, s[4:5]
	s_cbranch_execz .LBB0_2969
	s_branch .LBB0_2974

; DI float xhalf_sum(float v) { const auto r = __builtin_amdgcn_permlane32_swap(__float_as_uint(v), __float_as_uint(v), false, false); return __uint_as_float(r[0]) + __uint_as_float(r[1]); }
; DI void phase_index(const Params& p, unsigned char* lds) {
;     ...
;         auto proc = [&](auto PASSC, auto DIAGC, const f32x16& s, int k0, int kb) {
;             constexpr int PASS = decltype(PASSC)::value; constexpr bool DIAG = decltype(DIAGC)::value != 0;
;             f32x4 tot;
; #pragma unroll
;             for (int q = 0; q < 4; ++q) {
;                 float pr = 0.f;
; #pragma unroll
;                 for (int e = 0; e < 4; ++e) pr += wq[q][e] * fmaxf(s[4 * q + e], 0.f);
;                 tot[q] = xhalf_sum(pr);
;             }
;             const int key = k0 + 32 * kb + r32;
; #pragma unroll
;             for (int qq = 0; qq < 2; ++qq) {
;                 const float t_lo = tot[qq], t_hi = tot[2 + qq];
;                 const float sc = ((lane & 32) ? t_hi : t_lo) + 0.0f;
;                 const unsigned ub = __float_as_uint(sc);
;                 const unsigned uk = ub ^ ((unsigned)((int)ub >> 31) | 0x80000000u);
;                 const bool valid = DIAG ? (key <= tq0 + qq) : true;
;                 if (PASS == 0) {
;                     if (valid) { const unsigned a = (uk >> 21) & 0x7feu; atomicAdd((unsigned*)(lds + hbase0 + qq * 2048 + (a & ~3u)), 1u << ((a & 2u) << 3)); }
.LBB0_2977:
	v_max_f32_e32 v18, 0, v18
	v_fma_f32 v18, v50, v18, 0
	v_max_f32_e32 v19, 0, v19
	v_fmac_f32_e32 v18, v51, v19
	v_max_f32_e32 v19, 0, v20
	v_fmac_f32_e32 v18, v52, v19
	v_max_f32_e32 v19, 0, v21
	v_fmac_f32_e32 v18, v53, v19
	s_and_b64 vcc, exec, s[30:31]
	v_max_f32_e32 v105, v22, v22
	v_max_f32_e32 v104, v23, v23
	v_max_f32_e32 v103, v24, v24
	v_max_f32_e32 v102, v25, v25
	v_max_f32_e32 v26, v26, v26
	v_max_f32_e32 v25, v27, v27
	v_max_f32_e32 v24, v28, v28
	v_max_f32_e32 v23, v29, v29
	v_max_f32_e32 v22, v30, v30
	v_max_f32_e32 v21, v31, v31
	v_max_f32_e32 v20, v32, v32
	v_max_f32_e32 v19, v33, v33
	s_cbranch_vccz .LBB0_2980
	v_mov_b32_e32 v27, v18
	v_mov_b32_e32 v28, v18
	s_nop 1
	v_permlane32_swap_b32_e32 v27, v28
	v_add_f32_e32 v27, v27, v28
	v_max_f32_e32 v28, 0, v105
	v_max_f32_e32 v29, 0, v104
	v_pk_mul_f32 v[28:29], v[54:55], v[28:29]
	s_nop 0
	v_add_f32_e32 v28, 0, v28
	v_add_f32_e32 v30, v29, v28
	v_max_f32_e32 v28, 0, v103
	v_max_f32_e32 v29, 0, v102
	v_pk_mul_f32 v[28:29], v[56:57], v[28:29]
	s_mov_b64 s[30:31], -1
	v_add_f32_e32 v28, v28, v30
	v_add_f32_e32 v28, v29, v28
	v_mov_b32_e32 v29, v28
	s_nop 1
	v_permlane32_swap_b32_e32 v28, v29
	v_add_f32_e32 v30, v28, v29
	v_max_f32_e32 v28, 0, v26
	v_fma_f32 v28, v58, v28, 0
	v_max_f32_e32 v29, 0, v25
	v_fmac_f32_e32 v28, v59, v29
	v_max_f32_e32 v29, 0, v24
	v_fmac_f32_e32 v28, v60, v29
	v_max_f32_e32 v29, 0, v23
	v_fmac_f32_e32 v28, v61, v29
	v_mov_b32_e32 v29, v28
	s_nop 1
	v_permlane32_swap_b32_e32 v28, v29
	v_add_f32_e32 v31, v28, v29
	v_cndmask_b32_e64 v27, v31, v27, s[4:5]
	v_max_f32_e32 v28, 0, v22
	v_max_f32_e32 v29, 0, v21
	v_add_f32_e32 v27, 0, v27
	v_pk_mul_f32 v[28:29], v[62:63], v[28:29]
	v_ashrrev_i32_e32 v31, 31, v27
	v_add_f32_e32 v28, 0, v28
	v_bitop3_b32 v27, v31, v27, s82 bitop3:0x36
	v_add_f32_e32 v32, v29, v28
	v_max_f32_e32 v28, 0, v20
	v_max_f32_e32 v29, 0, v19
	v_lshrrev_b32_e32 v31, 21, v27
	v_lshrrev_b32_e32 v27, 18, v27
	v_pk_mul_f32 v[28:29], v[64:65], v[28:29]
	v_and_b32_e32 v31, 0x7fc, v31
	v_and_b32_e32 v27, 16, v27
	v_add_f32_e32 v28, v28, v32
	v_add_u32_e32 v31, v123, v31
	v_lshlrev_b32_e64 v27, v27, 1
	v_add_f32_e32 v28, v29, v28
	ds_add_u32 v31, v27
	v_mov_b32_e32 v29, v28
	s_nop 1
	v_permlane32_swap_b32_e32 v28, v29
	v_add_f32_e32 v27, v28, v29
	v_cndmask_b32_e64 v29, v27, v30, s[4:5]
	s_cbranch_execz .LBB0_2981
	s_branch .LBB0_2986

; #define MFMA32(a, b, c) __builtin_amdgcn_mfma_f32_32x32x16_bf16((a), (b), (c), 0, 0, 0)
; DI float xhalf_sum(float v) { const auto r = __builtin_amdgcn_permlane32_swap(__float_as_uint(v), __float_as_uint(v), false, false); return __uint_as_float(r[0]) + __uint_as_float(r[1]); }
; DI void phase_index(const Params& p, unsigned char* lds) {
;     ...
;         auto mma = [&](f32x16& s, unsigned off) {
; #pragma unroll
;             for (int i = 0; i < 16; ++i) s[i] = 0.f;
; #pragma unroll
;             for (int ks = 0; ks < 4; ++ks) { const bf16x8 kf = *(const bf16x8*)(lds + off + ks * 32); s = MFMA32(qf[ks], kf, s); }
;         };
;         auto proc = [&](auto PASSC, auto DIAGC, const f32x16& s, int k0, int kb) {
;             constexpr int PASS = decltype(PASSC)::value; constexpr bool DIAG = decltype(DIAGC)::value != 0;
;             f32x4 tot;
; #pragma unroll
;             for (int q = 0; q < 4; ++q) {
;                 float pr = 0.f;
; #pragma unroll
;                 for (int e = 0; e < 4; ++e) pr += wq[q][e] * fmaxf(s[4 * q + e], 0.f);
;                 tot[q] = xhalf_sum(pr);
;             }
;             const int key = k0 + 32 * kb + r32;
; #pragma unroll
;             for (int qq = 0; qq < 2; ++qq) {
;                 const float t_lo = tot[qq], t_hi = tot[2 + qq];
;                 const float sc = ((lane & 32) ? t_hi : t_lo) + 0.0f;
;                 const unsigned ub = __float_as_uint(sc);
;                 const unsigned uk = ub ^ ((unsigned)((int)ub >> 31) | 0x80000000u);
;                 const bool valid = DIAG ? (key <= tq0 + qq) : true;
;                 if (PASS == 0) {
;                     if (valid) { const unsigned a = (uk >> 21) & 0x7feu; atomicAdd((unsigned*)(lds + hbase0 + qq * 2048 + (a & ~3u)), 1u << ((a & 2u) << 3)); }
;                 } else if (PASS == 1) {
;                     if (valid && (int)(uk >> 22) == b1v[qq]) { const unsigned a = (uk >> 11) & 0x7feu; atomicAdd((unsigned*)(lds + hbase0 + qq * 2048 + (a & ~3u)), 1u << ((a & 2u) << 3)); }
.LBB0_3242:
	v_add_u32_e32 v115, s50, v113
	v_add_u32_e32 v18, 0x11200, v115
	ds_read_b128 v[18:21], v18
	v_add_u32_e32 v22, 0x11220, v115
	ds_read_b128 v[162:165], v22
	v_add_u32_e32 v167, 0x11240, v115
	s_waitcnt lgkmcnt(1)
	v_mfma_f32_32x32x16_bf16 v[18:33], v[42:45], v[18:21], 0
	v_max_f32_e32 v117, v3, v3
	v_max_f32_e32 v116, 0, v2
	v_max_f32_e32 v170, v6, v6
	v_max_f32_e32 v173, 0, v117
	v_fma_f32 v117, v50, v116, 0
	v_max_f32_e32 v172, v7, v7
	s_waitcnt lgkmcnt(0)
	v_mfma_f32_32x32x16_bf16 v[18:33], v[34:37], v[162:165], v[18:33]
	ds_read_b128 v[162:165], v167
	v_max_f32_e32 v161, 0, v4
	v_fmac_f32_e32 v117, v51, v173
	v_fmac_f32_e32 v117, v52, v161
	v_max_f32_e32 v161, 0, v8
	v_max_f32_e32 v166, v5, v5
	s_waitcnt lgkmcnt(0)
	v_mfma_f32_32x32x16_bf16 v[18:33], v[38:41], v[162:165], v[18:33]
	v_max_f32_e32 v162, 0, v170
	v_max_f32_e32 v163, 0, v172
	v_fma_f32 v116, v54, v162, 0
	v_fmac_f32_e32 v116, v55, v163
	v_fmac_f32_e32 v116, v56, v161
	v_max_f32_e32 v161, 0, v9
	v_fmac_f32_e32 v116, v57, v161
	v_max_f32_e32 v161, 0, v10
	v_add_u32_e32 v168, 0x11260, v115
	v_fma_f32 v162, v58, v161, 0
	v_max_f32_e32 v174, 0, v166
	ds_read_b128 v[166:169], v168
	v_max_f32_e32 v161, 0, v11
	v_fmac_f32_e32 v162, v59, v161
	v_max_f32_e32 v161, 0, v12
	v_fmac_f32_e32 v162, v60, v161
	v_max_f32_e32 v161, 0, v13
	s_waitcnt lgkmcnt(0)
	v_mfma_f32_32x32x16_bf16 v[18:33], v[46:49], v[166:169], v[18:33]
	v_fmac_f32_e32 v162, v61, v161
	v_max_f32_e32 v161, 0, v14
	v_fma_f32 v161, v62, v161, 0
	v_max_f32_e32 v163, 0, v15
	v_fmac_f32_e32 v161, v63, v163
	v_max_f32_e32 v163, 0, v16
	s_cmp_lg_u32 s0, s51
	v_fmac_f32_e32 v161, v64, v163
	s_cselect_b64 s[30:31], -1, 0
	v_max_f32_e32 v163, 0, v17
	v_fmac_f32_e32 v117, v53, v174
	v_fmac_f32_e32 v161, v65, v163
	s_and_b64 vcc, exec, s[30:31]
	s_cbranch_vccz .LBB0_3246
	v_mov_b32_e32 v163, v117
	v_mov_b32_e32 v164, v117
	v_mov_b32_e32 v165, v162
	v_mov_b32_e32 v166, v162
	v_permlane32_swap_b32_e32 v163, v164
	s_nop 0
	v_permlane32_swap_b32_e32 v165, v166
	v_add_f32_e32 v167, v163, v164
	v_add_f32_e32 v168, v165, v166
	v_cndmask_b32_e64 v167, v168, v167, s[4:5]
	v_add_f32_e32 v167, 0, v167
	v_ashrrev_i32_e32 v168, 31, v167
	v_bitop3_b32 v167, v168, v167, s82 bitop3:0x36
	v_mov_b32_e32 v163, v116
	v_mov_b32_e32 v164, v116
	v_mov_b32_e32 v165, v161
	v_mov_b32_e32 v166, v161
	v_lshrrev_b32_e32 v168, 22, v167
	v_permlane32_swap_b32_e32 v163, v164
	v_permlane32_swap_b32_e32 v165, v166
	v_cmp_eq_u32_e32 vcc, v168, v108
	s_and_saveexec_b64 s[26:27], vcc
	s_cbranch_execz .LBB0_3245
	v_lshrrev_b32_e32 v168, 11, v167
	v_lshrrev_b32_e32 v167, 8, v167
	v_and_b32_e32 v168, 0x7fc, v168
	v_and_b32_e32 v167, 16, v167
	v_add_u32_e32 v168, v123, v168
	v_lshlrev_b32_e64 v167, v167, 1
	ds_add_u32 v168, v167

; DI float xhalf_sum(float v) { const auto r = __builtin_amdgcn_permlane32_swap(__float_as_uint(v), __float_as_uint(v), false, false); return __uint_as_float(r[0]) + __uint_as_float(r[1]); }
; DI void phase_index(const Params& p, unsigned char* lds) {
;     ...
;         auto proc = [&](auto PASSC, auto DIAGC, const f32x16& s, int k0, int kb) {
;             constexpr int PASS = decltype(PASSC)::value; constexpr bool DIAG = decltype(DIAGC)::value != 0;
;             f32x4 tot;
; #pragma unroll
;             for (int q = 0; q < 4; ++q) {
;                 float pr = 0.f;
; #pragma unroll
;                 for (int e = 0; e < 4; ++e) pr += wq[q][e] * fmaxf(s[4 * q + e], 0.f);
;                 tot[q] = xhalf_sum(pr);
;             }
;             const int key = k0 + 32 * kb + r32;
; #pragma unroll
;             for (int qq = 0; qq < 2; ++qq) {
;                 const float t_lo = tot[qq], t_hi = tot[2 + qq];
;                 const float sc = ((lane & 32) ? t_hi : t_lo) + 0.0f;
;                 const unsigned ub = __float_as_uint(sc);
;                 const unsigned uk = ub ^ ((unsigned)((int)ub >> 31) | 0x80000000u);
;                 const bool valid = DIAG ? (key <= tq0 + qq) : true;
;                 if (PASS == 0) {
;                     if (valid) { const unsigned a = (uk >> 21) & 0x7feu; atomicAdd((unsigned*)(lds + hbase0 + qq * 2048 + (a & ~3u)), 1u << ((a & 2u) << 3)); }
;                 } else if (PASS == 1) {
;                     if (valid && (int)(uk >> 22) == b1v[qq]) { const unsigned a = (uk >> 11) & 0x7feu; atomicAdd((unsigned*)(lds + hbase0 + qq * 2048 + (a & ~3u)), 1u << ((a & 2u) << 3)); }
.LBB0_3254:
	v_max_f32_e32 v18, 0, v18
	v_fma_f32 v115, v50, v18, 0
	v_max_f32_e32 v18, 0, v19
	v_fmac_f32_e32 v115, v51, v18
	v_max_f32_e32 v18, 0, v20
	v_fmac_f32_e32 v115, v52, v18
	v_max_f32_e32 v18, 0, v21
	v_fmac_f32_e32 v115, v53, v18
	v_max_f32_e32 v18, 0, v22
	v_fma_f32 v18, v54, v18, 0
	v_max_f32_e32 v19, 0, v23
	v_fmac_f32_e32 v18, v55, v19
	v_max_f32_e32 v19, 0, v24
	v_fmac_f32_e32 v18, v56, v19
	v_max_f32_e32 v19, 0, v25
	v_fmac_f32_e32 v18, v57, v19
	v_max_f32_e32 v19, 0, v26
	v_fma_f32 v20, v58, v19, 0
	v_max_f32_e32 v19, 0, v27
	v_fmac_f32_e32 v20, v59, v19
	v_max_f32_e32 v19, 0, v28
	v_fmac_f32_e32 v20, v60, v19
	v_max_f32_e32 v19, 0, v29
	v_fmac_f32_e32 v20, v61, v19
	v_max_f32_e32 v19, 0, v30
	v_fma_f32 v19, v62, v19, 0
	v_max_f32_e32 v21, 0, v31
	v_fmac_f32_e32 v19, v63, v21
	v_max_f32_e32 v21, 0, v32
	v_fmac_f32_e32 v19, v64, v21
	v_max_f32_e32 v21, 0, v33
	v_fmac_f32_e32 v19, v65, v21
	s_and_b64 vcc, exec, s[30:31]
	s_cbranch_vccz .LBB0_3259
	v_mov_b32_e32 v21, v115
	v_mov_b32_e32 v22, v115
	v_mov_b32_e32 v23, v20
	v_mov_b32_e32 v24, v20
	v_permlane32_swap_b32_e32 v21, v22
	s_nop 0
	v_permlane32_swap_b32_e32 v23, v24
	v_add_f32_e32 v25, v21, v22
	v_add_f32_e32 v26, v23, v24
	v_cndmask_b32_e64 v25, v26, v25, s[4:5]
	v_add_f32_e32 v25, 0, v25
	v_ashrrev_i32_e32 v26, 31, v25
	v_bitop3_b32 v25, v26, v25, s82 bitop3:0x36
	v_mov_b32_e32 v21, v18
	v_mov_b32_e32 v22, v18
	v_mov_b32_e32 v23, v19
	v_mov_b32_e32 v24, v19
	v_lshrrev_b32_e32 v26, 22, v25
	v_permlane32_swap_b32_e32 v21, v22
	v_permlane32_swap_b32_e32 v23, v24
	v_cmp_eq_u32_e32 vcc, v26, v108
	s_and_saveexec_b64 s[26:27], vcc
	s_cbranch_execz .LBB0_3257
	v_lshrrev_b32_e32 v26, 11, v25
	v_lshrrev_b32_e32 v25, 8, v25
	v_and_b32_e32 v26, 0x7fc, v26
	v_and_b32_e32 v25, 16, v25
	v_add_u32_e32 v26, v123, v26
	v_lshlrev_b32_e64 v25, v25, 1
	ds_add_u32 v26, v25

; #define MFMA32(a, b, c) __builtin_amdgcn_mfma_f32_32x32x16_bf16((a), (b), (c), 0, 0, 0)
; DI float xhalf_sum(float v) { const auto r = __builtin_amdgcn_permlane32_swap(__float_as_uint(v), __float_as_uint(v), false, false); return __uint_as_float(r[0]) + __uint_as_float(r[1]); }
; DI void phase_index(const Params& p, unsigned char* lds) {
;     ...
;         auto mma = [&](f32x16& s, unsigned off) {
; #pragma unroll
;             for (int i = 0; i < 16; ++i) s[i] = 0.f;
; #pragma unroll
;             for (int ks = 0; ks < 4; ++ks) { const bf16x8 kf = *(const bf16x8*)(lds + off + ks * 32); s = MFMA32(qf[ks], kf, s); }
;         };
;         auto proc = [&](auto PASSC, auto DIAGC, const f32x16& s, int k0, int kb) {
;             constexpr int PASS = decltype(PASSC)::value; constexpr bool DIAG = decltype(DIAGC)::value != 0;
;             f32x4 tot;
; #pragma unroll
;             for (int q = 0; q < 4; ++q) {
;                 float pr = 0.f;
; #pragma unroll
;                 for (int e = 0; e < 4; ++e) pr += wq[q][e] * fmaxf(s[4 * q + e], 0.f);
;                 tot[q] = xhalf_sum(pr);
.LBB0_3520:
	s_mul_i32 s26, s1, 0x2400
	v_add_u32_e32 v163, s26, v161
	ds_read_b128 v[18:21], v163 offset:4608
	ds_read_b128 v[114:117], v163 offset:4640
	s_nop 2
	v_max_f32_e32 v164, v2, v2
	v_max_f32_e32 v165, v3, v3
	s_waitcnt lgkmcnt(1)
	v_mfma_f32_32x32x16_bf16 v[18:33], v[42:45], v[18:21], 0
	v_max_f32_e32 v166, v4, v4
	v_max_f32_e32 v167, v5, v5
	v_max_f32_e32 v168, 0, v6
	v_max_f32_e32 v170, v8, v8
	v_max_f32_e32 v172, 0, v164
	v_max_f32_e32 v173, 0, v165
	s_waitcnt lgkmcnt(0)
	v_mfma_f32_32x32x16_bf16 v[18:33], v[34:37], v[114:117], v[18:33]
	ds_read_b128 v[114:117], v163 offset:4672
	v_max_f32_e32 v174, 0, v166
	v_max_f32_e32 v175, 0, v167
	v_max_f32_e32 v169, 0, v7
	ds_read_b128 v[164:167], v163 offset:4704
	s_add_i32 s36, s1, s96
	s_cmp_lg_u32 s36, s91
	s_waitcnt lgkmcnt(1)
	v_mfma_f32_32x32x16_bf16 v[18:33], v[38:41], v[114:117], v[18:33]
	v_fma_f32 v115, v54, v168, 0
	v_fmac_f32_e32 v115, v55, v169
	v_max_f32_e32 v116, 0, v170
	v_fmac_f32_e32 v115, v56, v116
	v_max_f32_e32 v116, 0, v9
	v_fmac_f32_e32 v115, v57, v116
	v_max_f32_e32 v116, 0, v10
	v_fma_f32 v116, v58, v116, 0
	v_max_f32_e32 v117, 0, v11
	v_fmac_f32_e32 v116, v59, v117
	v_max_f32_e32 v117, 0, v12
	v_fmac_f32_e32 v116, v60, v117
	v_max_f32_e32 v117, 0, v13
	s_waitcnt lgkmcnt(0)
	v_mfma_f32_32x32x16_bf16 v[18:33], v[46:49], v[164:167], v[18:33]
	v_fmac_f32_e32 v116, v61, v117
	v_max_f32_e32 v117, 0, v14
	v_fma_f32 v117, v62, v117, 0
	v_max_f32_e32 v164, 0, v15
	v_fmac_f32_e32 v117, v63, v164
	v_fma_f32 v114, v50, v172, 0
	v_max_f32_e32 v164, 0, v16
	v_fmac_f32_e32 v114, v51, v173
	v_fmac_f32_e32 v117, v64, v164
	s_cselect_b64 s[58:59], -1, 0
	v_fmac_f32_e32 v114, v52, v174
	v_max_f32_e32 v164, 0, v17
	v_fmac_f32_e32 v114, v53, v175
	v_fmac_f32_e32 v117, v65, v164
	s_mov_b64 s[26:27], -1
	s_and_b64 vcc, exec, s[58:59]
	s_cbranch_vccnz .LBB0_3555
	s_lshl_b32 s28, s36, 6
	s_andn2_b64 vcc, exec, s[26:27]
	v_or_b32_e32 v164, s28, v194
	s_cbranch_vccz .LBB0_3556

; DI void phase_index(const Params& p, unsigned char* lds) {
;     ...
;         auto proc = [&](auto PASSC, auto DIAGC, const f32x16& s, int k0, int kb) {
;             constexpr int PASS = decltype(PASSC)::value; constexpr bool DIAG = decltype(DIAGC)::value != 0;
;             f32x4 tot;
; #pragma unroll
;             for (int q = 0; q < 4; ++q) {
;                 float pr = 0.f;
; #pragma unroll
;                 for (int e = 0; e < 4; ++e) pr += wq[q][e] * fmaxf(s[4 * q + e], 0.f);
;                 tot[q] = xhalf_sum(pr);
;             }
;             const int key = k0 + 32 * kb + r32;
; #pragma unroll
;             for (int qq = 0; qq < 2; ++qq) {
;                 const float t_lo = tot[qq], t_hi = tot[2 + qq];
;                 const float sc = ((lane & 32) ? t_hi : t_lo) + 0.0f;
;                 const unsigned ub = __float_as_uint(sc);
;                 const unsigned uk = ub ^ ((unsigned)((int)ub >> 31) | 0x80000000u);
;                 const bool valid = DIAG ? (key <= tq0 + qq) : true;
;                 if (PASS == 0) {
;                     if (valid) { const unsigned a = (uk >> 21) & 0x7feu; atomicAdd((unsigned*)(lds + hbase0 + qq * 2048 + (a & ~3u)), 1u << ((a & 2u) << 3)); }
;                 } else if (PASS == 1) {
;                     if (valid && (int)(uk >> 22) == b1v[qq]) { const unsigned a = (uk >> 11) & 0x7feu; atomicAdd((unsigned*)(lds + hbase0 + qq * 2048 + (a & ~3u)), 1u << ((a & 2u) << 3)); }
;                 } else if (PASS == 3) {
;                     if (valid) {
;                         const int k10 = (int)(uk >> 22), d = k10 - b1v[qq];
;                         if (k10 > hiv[qq]) cntA[qq] += 1;
;                         else if (d >= 0) {
;                             const unsigned bin = ((unsigned)d << sbv[qq]) | ((uk >> (22 - sbv[qq])) & ((1u << sbv[qq]) - 1u));
;                             const unsigned a = bin << 1;
;                             atomicAdd((unsigned*)(lds + hbase0 + qq * 2048 + (a & ~3u)), 1u << ((a & 2u) << 3));
;                         }
;                     }
;                 } else {
;                     const int k20 = (int)(uk >> kshv[qq]);
;                     const u64 bg = __ballot(valid && k20 > tauv[qq]);
;                     const u64 be = __ballot(valid && k20 == tauv[qq]);
;                     Gm[qq] |= (bg & 0xffffffffull) << (32 * kb); Gm[2 + qq] |= (bg >> 32) << (32 * kb);
.LBB0_3524:
	v_max_f32_e32 v18, 0, v18
	v_fma_f32 v18, v50, v18, 0
	v_max_f32_e32 v19, 0, v19
	v_fmac_f32_e32 v18, v51, v19
	v_max_f32_e32 v19, 0, v20
	v_fmac_f32_e32 v18, v52, v19
	v_max_f32_e32 v19, 0, v21
	v_fmac_f32_e32 v18, v53, v19
	v_max_f32_e32 v19, 0, v22
	v_fma_f32 v19, v54, v19, 0
	v_max_f32_e32 v20, 0, v23
	v_fmac_f32_e32 v19, v55, v20
	v_max_f32_e32 v20, 0, v24
	v_fmac_f32_e32 v19, v56, v20
	v_max_f32_e32 v20, 0, v25
	v_fmac_f32_e32 v19, v57, v20
	v_max_f32_e32 v20, 0, v26
	v_fma_f32 v20, v58, v20, 0
	v_max_f32_e32 v21, 0, v27
	v_fmac_f32_e32 v20, v59, v21
	v_max_f32_e32 v21, 0, v28
	v_fmac_f32_e32 v20, v60, v21
	v_max_f32_e32 v21, 0, v29
	v_fmac_f32_e32 v20, v61, v21
	v_max_f32_e32 v21, 0, v30
	v_fma_f32 v21, v62, v21, 0
	v_max_f32_e32 v22, 0, v31
	v_fmac_f32_e32 v21, v63, v22
	v_max_f32_e32 v22, 0, v32
	v_fmac_f32_e32 v21, v64, v22
	v_max_f32_e32 v22, 0, v33
	v_fmac_f32_e32 v21, v65, v22
	s_mov_b64 s[28:29], -1
	s_and_b64 vcc, exec, s[58:59]
	s_cbranch_vccz .LBB0_3526
	v_mov_b32_e32 v22, v18
	v_mov_b32_e32 v24, v18
	v_mov_b32_e32 v23, v19
	v_mov_b32_e32 v25, v19
	v_mov_b32_e32 v26, v20
	v_mov_b32_e32 v28, v20
	v_mov_b32_e32 v27, v21
	v_mov_b32_e32 v29, v21
	v_permlane32_swap_b32_e32 v22, v24
	v_permlane32_swap_b32_e32 v23, v25
	v_permlane32_swap_b32_e32 v26, v28
	v_permlane32_swap_b32_e32 v27, v29
	v_pk_add_f32 v[22:23], v[22:23], v[24:25]
	v_pk_add_f32 v[24:25], v[26:27], v[28:29]
	s_mov_b64 s[28:29], 0
	v_cndmask_b32_e64 v23, v25, v23, s[4:5]
	v_cndmask_b32_e64 v22, v24, v22, s[4:5]
	v_pk_add_f32 v[22:23], v[22:23], 0 op_sel_hi:[1,0]
	s_nop 0
	v_ashrrev_i32_e32 v24, 31, v23
	v_ashrrev_i32_e32 v25, 31, v22
	v_or_b32_e32 v24, 0x80000000, v24
	v_or_b32_e32 v25, 0x80000000, v25
	v_xor_b32_e32 v23, v24, v23
	v_xor_b32_e32 v22, v25, v22
	v_lshrrev_b32_e32 v23, v83, v23
	v_lshrrev_b32_e32 v22, v106, v22
	v_cmp_gt_i32_e64 s[58:59], v22, v100
	v_cmp_eq_u32_e64 s[68:69], v22, v100
	v_cmp_gt_i32_e64 s[30:31], v23, v1
	v_cmp_eq_u32_e64 s[26:27], v23, v1
